# attention loops 1 and 2: first-half K/V prefetch-issue block moved after the next tile's LDS fragment reads
# baseline (speedup 1.0000x reference)
.LBB0_1458:
	s_add_i32 s2, s28, -2
	s_and_b32 s2, s2, 3
	s_mulk_i32 s2, 0x3000
	v_add_u32_e32 v52, s2, v170
	ds_read_b128 v[48:51], v52
	ds_read_b128 v[164:167], v52 offset:512
	ds_read_b128 v[180:183], v52 offset:2048
	ds_read_b128 v[184:187], v52 offset:2560
	ds_read_b128 v[196:199], v52 offset:4096
	ds_read_b128 v[200:203], v52 offset:4608
	ds_read_b128 v[204:207], v52 offset:6144
	ds_read_b128 v[208:211], v52 offset:6656
	ds_read_b128 v[218:221], v52 offset:8192
	ds_read_b128 v[222:225], v52 offset:8704
	ds_read_b128 v[226:229], v52 offset:10240
	ds_read_b128 v[230:233], v52 offset:10752
	s_add_i32 s2, s29, 0xffffa000
	s_and_b32 s2, s2, 0x6000
	v_add_f32_e32 v52, v96, v97
	v_add_u32_e32 v179, s2, v175
	ds_read_b64_tr_b16 v[160:161], v179 offset:49152
	ds_read_b64_tr_b16 v[162:163], v179 offset:49664
	s_and_b64 vcc, exec, s[48:49]
	s_cbranch_vccnz .Latt2_nopf
	s_cmp_gt_u32 s33, 4
	s_cselect_b32 s2, s77, 0
	s_add_i32 s2, s2, s28
	s_lshl_b32 s2, s2, 6
	s_add_i32 s50, s2, s72
	s_and_b32 s2, s28, 3
	s_mul_i32 s3, s2, 0x3000
	s_mul_hi_i32 s37, s50, s39
	s_mul_i32 s36, s50, s39
	s_add_i32 s3, s3, 0
	v_lshl_add_u64 v[54:55], s[36:37], 1, v[190:191]
	s_add_i32 s33, s3, s86
	s_mov_b32 s51, m0
	s_mov_b32 m0, s33
	s_nop 0
	global_load_lds_dwordx4 v[54:55], off
	s_mov_b32 m0, s51
	s_and_b64 vcc, exec, s[4:5]
	s_cbranch_vccnz .LBB0_1457
	s_ashr_i32 s51, s50, 31
	s_lshl_b64 s[50:51], s[50:51], 6
	s_add_i32 s3, s3, s84
	v_lshl_add_u64 v[54:55], v[114:115], 0, s[50:51]
	s_mov_b32 s33, m0
	s_mov_b32 m0, s3
	s_nop 0
	global_load_lds_dwordx4 v[54:55], off
	s_mov_b32 m0, s33
.LBB0_1457:
	s_lshl_b32 s2, s2, 13
	v_lshl_add_u64 v[54:55], s[36:37], 1, v[168:169]
	s_add_i32 s2, s2, s83
	s_mov_b32 s3, m0
	s_mov_b32 m0, s2
	s_nop 0
	global_load_lds_dwordx4 v[54:55], off
	s_mov_b32 m0, s3
.Latt2_nopf:
	s_waitcnt lgkmcnt(13)
	v_mfma_f32_32x32x16_bf16 v[64:79], v[48:51], v[136:139], v[32:47]
	v_add_f32_e32 v52, v98, v52
	v_add_f32_e32 v52, v99, v52
	v_add_f32_e32 v52, v100, v52
	v_cvt_pk_bf16_f32 v148, v96, v97
	v_cvt_pk_bf16_f32 v149, v98, v99
	ds_read_b64_tr_b16 v[156:157], v179 offset:53248
	ds_read_b64_tr_b16 v[158:159], v179 offset:53760
	v_add_f32_e32 v48, v101, v52
	v_add_f32_e32 v48, v102, v48
	v_add_f32_e32 v140, v103, v48
	s_waitcnt lgkmcnt(14)
	v_mfma_f32_32x32x16_bf16 v[48:63], v[164:167], v[136:139], v[32:47]
	v_cvt_pk_bf16_f32 v150, v100, v101
	v_cvt_pk_bf16_f32 v151, v102, v103
	ds_read_b64_tr_b16 v[96:97], v179 offset:50176
	ds_read_b64_tr_b16 v[98:99], v179 offset:50688
	s_waitcnt lgkmcnt(14)
	v_mfma_f32_32x32x16_bf16 v[64:79], v[180:183], v[132:135], v[64:79]
	v_add_f32_e32 v100, v104, v140
	v_add_f32_e32 v100, v105, v100
	v_add_f32_e32 v140, v106, v100
	v_cvt_pk_bf16_f32 v152, v104, v105
	v_cvt_pk_bf16_f32 v153, v106, v107
	ds_read_b64_tr_b16 v[100:101], v179 offset:54272
	ds_read_b64_tr_b16 v[102:103], v179 offset:54784
	v_mfma_f32_32x32x16_bf16 v[48:63], v[184:187], v[132:135], v[48:63]
	v_add_f32_e32 v104, v107, v140
	v_add_f32_e32 v104, v108, v104
	v_add_f32_e32 v140, v109, v104
	v_cvt_pk_bf16_f32 v154, v108, v109
	v_cvt_pk_bf16_f32 v155, v110, v111
	ds_read_b64_tr_b16 v[104:105], v179 offset:51200
	ds_read_b64_tr_b16 v[106:107], v179 offset:51712
	s_waitcnt lgkmcnt(14)
	v_mfma_f32_32x32x16_bf16 v[64:79], v[196:199], v[128:131], v[64:79]
	v_add_f32_e32 v108, v110, v140
	v_add_f32_e32 v108, v111, v108
	v_add_f32_e32 v140, v80, v108
	v_cvt_pk_bf16_f32 v144, v80, v81
	v_cvt_pk_bf16_f32 v145, v82, v83
	ds_read_b64_tr_b16 v[108:109], v179 offset:55296
	ds_read_b64_tr_b16 v[110:111], v179 offset:55808
	v_mfma_f32_32x32x16_bf16 v[48:63], v[200:203], v[128:131], v[48:63]
	v_add_f32_e32 v80, v81, v140
	v_add_f32_e32 v80, v82, v80
	v_add_f32_e32 v140, v83, v80
	v_cvt_pk_bf16_f32 v146, v84, v85
	v_cvt_pk_bf16_f32 v147, v86, v87
	ds_read_b64_tr_b16 v[80:81], v179 offset:52224
	ds_read_b64_tr_b16 v[82:83], v179 offset:52736
	v_mfma_f32_32x32x16_bf16 v[64:79], v[204:207], v[124:127], v[64:79]
	v_add_f32_e32 v84, v84, v140
	v_add_f32_e32 v84, v85, v84
	v_add_f32_e32 v84, v86, v84
	v_cvt_pk_bf16_f32 v140, v88, v89
	v_cvt_pk_bf16_f32 v141, v90, v91
	ds_read_b64_tr_b16 v[164:165], v179 offset:56320
	ds_read_b64_tr_b16 v[166:167], v179 offset:56832
	v_mfma_f32_32x32x16_bf16 v[48:63], v[208:211], v[124:127], v[48:63]
	v_add_f32_e32 v84, v87, v84
	v_add_f32_e32 v84, v88, v84
	v_add_f32_e32 v84, v89, v84
	v_cvt_pk_bf16_f32 v142, v92, v93
	v_cvt_pk_bf16_f32 v143, v94, v95
	s_waitcnt lgkmcnt(14)
	v_mfma_f32_32x32x16_bf16 v[64:79], v[218:221], v[120:123], v[64:79]
	v_add_f32_e32 v84, v90, v84
	v_add_f32_e32 v84, v91, v84
	v_add_f32_e32 v84, v92, v84
	v_mfma_f32_32x32x16_bf16 v[48:63], v[222:225], v[120:123], v[48:63]
	v_add_f32_e32 v84, v93, v84
	v_add_f32_e32 v84, v94, v84
	v_add_f32_e32 v84, v95, v84
	v_mfma_f32_32x32x16_bf16 v[64:79], v[226:229], v[116:119], v[64:79]
	v_mfma_f32_32x32x16_bf16 v[48:63], v[230:233], v[116:119], v[48:63]
	s_nop 10
	v_max_f32_e32 v85, v64, v65
	v_max3_f32 v86, v66, v67, v49
	v_max3_f32 v85, v85, v48, v50
	v_max3_f32 v85, v85, v51, v68
	v_max3_f32 v86, v86, v70, v71
	v_max3_f32 v85, v85, v69, v52
	v_max3_f32 v86, v86, v54, v55
	v_max3_f32 v85, v85, v53, v72
	v_max3_f32 v86, v86, v74, v75
	v_max3_f32 v85, v85, v73, v56
	v_max3_f32 v86, v86, v58, v59
	v_max3_f32 v85, v85, v57, v76
	v_max3_f32 v86, v86, v78, v79
	v_max3_f32 v85, v85, v77, v60
	v_max3_f32 v86, v86, v62, v63
	v_add_f32_e32 v178, v178, v84
	v_max3_f32 v84, v85, v61, v86
	v_mov_b32_e32 v85, v84
	s_nop 1
	v_permlane32_swap_b32 v85, v84
	s_nop 1
	s_nop 0
	v_max_f32_e32 v84, v85, v84
	v_cmp_lt_f32_e32 vcc, s92, v84
	s_cmp_lg_u64 vcc, 0
	s_cselect_b64 s[50:51], -1, 0
	s_cbranch_vccnz .LBB0_1474
